# DIFF fast path: PV chains use 6/7-deep V-fragment rings in dead K-fragment VGPRs with counted lgkmcnt, ALiBi(sub1) spread 2 VALU per MFMA
# speedup vs baseline: 1.0498x; 1.0051x over previous
; #define MFMA(a, b, c) __builtin_amdgcn_mfma_f32_32x32x16_bf16((a), (b), (c), 0, 0, 0)
; DI u32 pk2(float a, float b) { f2_t v = {a, b}; bf2_t r = __builtin_convertvector(v, bf2_t); return __builtin_bit_cast(u32, r); }
; #define DIFF_MASK(sv, sub_) do { if (needmask) { _Pragma("unroll") for (int r = 0; r < 16; ++r) { const int kl_ = (sub_) * 32 + ((r < 8) ? (8 * g2 + r) : (16 + 8 * g2 + (r - 8))); \
;           if ((pki[kl_] >> 6) > (((int)qposf) >> 6)) sv[r] = -__builtin_inff(); } } } while (0)
; template <bool DIFF>
; DI void attn_phase(const AttnArgs& a, char* lds) {
;     ...
;           float ps = 0.f;
; #pragma unroll
;           for (int r = 0; r < 16; ++r) { s0[r] = __builtin_amdgcn_exp2f(s0[r]); ps += s0[r]; }
;           l_sum += ps;
;           asm volatile("" : "+v"(l_sum));
; #pragma unroll
;           for (int i = 0; i < NDS; ++i) { __builtin_amdgcn_sched_group_barrier(0x008, 1, 0); __builtin_amdgcn_sched_group_barrier(0x002, 9, 0); }
;         }
;         __builtin_amdgcn_sched_barrier(0);
;         {
;           bf16x8 vf[NM];
; #pragma unroll
;           for (int s2 = 0; s2 < 2; ++s2) {
; #pragma unroll
;             for (int m = 0; m < NM; ++m) vf[m] = *(const bf16x8*)(sb + voffb + m * 4096 + (((2 * s2) ^ vx) << 4));
;             u32x4 pw;
;             pw[0] = pk2(s0[8 * s2], s0[8 * s2 + 1]); pw[1] = pk2(s0[8 * s2 + 2], s0[8 * s2 + 3]);
;             pw[2] = pk2(s0[8 * s2 + 4], s0[8 * s2 + 5]); pw[3] = pk2(s0[8 * s2 + 6], s0[8 * s2 + 7]);
;             const bf16x8 pf = __builtin_bit_cast(bf16x8, pw);
; #pragma unroll
;             for (int m = 0; m < NM; ++m) o[m] = MFMA(vf[m], pf, o[m]);
;           }
;           DIFF_ALIBI(s1, 1);
;           DIFF_MASK(s1, 1);
.LBB0_605:
	v_exp_f32_e32 v11, v11
	v_exp_f32_e32 v9, v9
	v_exp_f32_e32 v10, v10
	v_exp_f32_e32 v8, v8
	v_bitop3_b32 v0, v0, v3, 7 bitop3:0x78
	v_add_f32_e32 v3, 0, v11
	v_exp_f32_e32 v165, v7
	v_add_f32_e32 v3, v9, v3
	v_exp_f32_e32 v166, v6
	v_add_f32_e32 v3, v10, v3
	v_exp_f32_e32 v167, v5
	v_add_f32_e32 v3, v8, v3
	v_exp_f32_e32 v168, v4
	v_add_f32_e32 v3, v165, v3
	v_exp_f32_e32 v164, v164
	v_lshlrev_b32_e32 v2, 7, v2
	v_add_f32_e32 v3, v166, v3
	v_exp_f32_e32 v169, v162
	v_and_b32_e32 v2, 0xf80, v2
	v_add_f32_e32 v3, v167, v3
	v_exp_f32_e32 v170, v160
	v_add_f32_e32 v3, v168, v3
	v_exp_f32_e32 v171, v161
	v_add_f32_e32 v3, v164, v3
	v_exp_f32_e32 v15, v15
	v_add_f32_e32 v3, v169, v3
	v_exp_f32_e32 v14, v14
	v_add_f32_e32 v3, v170, v3
	v_exp_f32_e32 v172, v13
	v_add_f32_e32 v3, v171, v3
	v_exp_f32_e32 v173, v12
	v_add_f32_e32 v3, v15, v3
	v_add_f32_e32 v3, v14, v3
	v_add_f32_e32 v3, v172, v3
	v_add_f32_e32 v3, v173, v3
	v_add_f32_e32 v162, v226, v3
	v_add_u32_e32 v160, s84, v2
	v_lshlrev_b32_e32 v161, 4, v0
	v_add_u32_e32 v0, v160, v161
	v_cvt_pk_bf16_f32 v6, v11, v9
	v_cvt_pk_bf16_f32 v7, v10, v8
	v_cvt_pk_bf16_f32 v8, v165, v166
	v_cvt_pk_bf16_f32 v9, v167, v168
	v_cvt_pk_bf16_f32 v10, v164, v169
	v_cvt_pk_bf16_f32 v11, v170, v171
	v_cvt_pk_bf16_f32 v12, v15, v14
	v_cvt_pk_bf16_f32 v13, v172, v173
	v_add_u32_e32 v14, 0x10180, v227
	v_xad_u32 v15, v161, 32, v160
	ds_read_b128 v[164:167], v14
	ds_read_b128 v[168:171], v14 offset:16
	ds_read_b128 v[172:175], v14 offset:64
	ds_read_b128 v[248:251], v14 offset:80
	ds_read_b128 v[2:5], v0 offset:32768
	ds_read_b128 v[228:231], v0 offset:36864
	ds_read_b128 v[232:235], v0 offset:40960
	ds_read_b128 v[236:239], v0 offset:45056
	ds_read_b128 v[240:243], v0 offset:49152
	ds_read_b128 v[244:247], v0 offset:53248
	s_and_b64 vcc, exec, s[8:9]
	s_waitcnt lgkmcnt(5)
	v_mfma_f32_32x32x16_bf16 v[128:143], v[2:5], v[6:9], v[128:143]
	ds_read_b128 v[2:5], v0 offset:57344
	v_sub_f32_e32 v164, v221, v164
	v_sub_f32_e32 v165, v221, v165
	s_waitcnt lgkmcnt(5)
	v_mfma_f32_32x32x16_bf16 v[112:127], v[228:231], v[6:9], v[112:127]
	ds_read_b128 v[228:231], v0 offset:61440
	v_sub_f32_e32 v166, v221, v166
	v_sub_f32_e32 v167, v221, v167
	s_waitcnt lgkmcnt(5)
	v_mfma_f32_32x32x16_bf16 v[96:111], v[232:235], v[6:9], v[96:111]
	ds_read_b128 v[232:235], v15 offset:32768
	v_sub_f32_e32 v168, v221, v168
	v_sub_f32_e32 v169, v221, v169
	s_waitcnt lgkmcnt(5)
	v_mfma_f32_32x32x16_bf16 v[80:95], v[236:239], v[6:9], v[80:95]
	ds_read_b128 v[236:239], v15 offset:36864
	v_sub_f32_e32 v170, v221, v170
	v_sub_f32_e32 v171, v221, v171
	s_waitcnt lgkmcnt(5)
	v_mfma_f32_32x32x16_bf16 v[64:79], v[240:243], v[6:9], v[64:79]
	ds_read_b128 v[240:243], v15 offset:40960
	v_sub_f32_e32 v172, v221, v172
	v_sub_f32_e32 v173, v221, v173
	s_waitcnt lgkmcnt(5)
	v_mfma_f32_32x32x16_bf16 v[48:63], v[244:247], v[6:9], v[48:63]
	ds_read_b128 v[244:247], v15 offset:45056
	v_sub_f32_e32 v174, v221, v174
	v_sub_f32_e32 v175, v221, v175
	s_waitcnt lgkmcnt(5)
	v_mfma_f32_32x32x16_bf16 v[32:47], v[2:5], v[6:9], v[32:47]
	ds_read_b128 v[2:5], v15 offset:49152
	v_sub_f32_e32 v248, v221, v248
	v_sub_f32_e32 v249, v221, v249
	s_waitcnt lgkmcnt(5)
	v_mfma_f32_32x32x16_bf16 v[16:31], v[228:231], v[6:9], v[16:31]
	ds_read_b128 v[228:231], v15 offset:53248
	v_sub_f32_e32 v250, v221, v250
	v_sub_f32_e32 v251, v221, v251
	s_waitcnt lgkmcnt(5)
	v_mfma_f32_32x32x16_bf16 v[128:143], v[232:235], v[10:13], v[128:143]
	ds_read_b128 v[232:235], v15 offset:57344
	v_fma_f32 v164, -v223, |v164|, v144
	v_fma_f32 v165, -v223, |v165|, v145
	s_waitcnt lgkmcnt(5)
	v_mfma_f32_32x32x16_bf16 v[112:127], v[236:239], v[10:13], v[112:127]
	ds_read_b128 v[236:239], v15 offset:61440
	v_fma_f32 v166, -v223, |v166|, v146
	v_fma_f32 v167, -v223, |v167|, v147
	s_waitcnt lgkmcnt(5)
	v_mfma_f32_32x32x16_bf16 v[96:111], v[240:243], v[10:13], v[96:111]
	v_fma_f32 v168, -v223, |v168|, v148
	v_fma_f32 v169, -v223, |v169|, v149
	s_waitcnt lgkmcnt(4)
	v_mfma_f32_32x32x16_bf16 v[80:95], v[244:247], v[10:13], v[80:95]
	v_fma_f32 v170, -v223, |v170|, v150
	v_fma_f32 v171, -v223, |v171|, v151
	s_waitcnt lgkmcnt(3)
	v_mfma_f32_32x32x16_bf16 v[64:79], v[2:5], v[10:13], v[64:79]
	v_fma_f32 v172, -v223, |v172|, v152
	v_fma_f32 v173, -v223, |v173|, v153
	s_waitcnt lgkmcnt(2)
	v_mfma_f32_32x32x16_bf16 v[48:63], v[228:231], v[10:13], v[48:63]
	v_fma_f32 v174, -v223, |v174|, v154
	v_fma_f32 v175, -v223, |v175|, v155
	s_waitcnt lgkmcnt(1)
	v_mfma_f32_32x32x16_bf16 v[32:47], v[232:235], v[10:13], v[32:47]
	v_fma_f32 v248, -v223, |v248|, v156
	v_fma_f32 v249, -v223, |v249|, v157
	s_waitcnt lgkmcnt(0)
	v_mfma_f32_32x32x16_bf16 v[16:31], v[236:239], v[10:13], v[16:31]
	v_fma_f32 v250, -v223, |v250|, v158
	v_fma_f32 v251, -v223, |v251|, v159
	s_cbranch_vccnz .LBB0_607
	ds_read_b128 v[146:149], v163 offset:128
	s_waitcnt lgkmcnt(0)
	v_ashrrev_i32_e32 v144, 6, v146
	v_cmp_le_i32_e32 vcc, v144, v224
	v_ashrrev_i32_e32 v144, 6, v147
	s_nop 0
	v_cndmask_b32_e32 v164, v216, v164, vcc
	v_cmp_le_i32_e32 vcc, v144, v224
	v_ashrrev_i32_e32 v144, 6, v148
	s_nop 0
	v_cndmask_b32_e32 v165, v216, v165, vcc
	v_cmp_le_i32_e32 vcc, v144, v224
	v_ashrrev_i32_e32 v144, 6, v149
	s_nop 0
	v_cndmask_b32_e32 v166, v216, v166, vcc
	v_cmp_le_i32_e32 vcc, v144, v224
	v_add_u32_e32 v144, 0x10090, v227
	ds_read_b128 v[146:149], v144
	v_cndmask_b32_e32 v167, v216, v167, vcc
	s_waitcnt lgkmcnt(0)
	v_ashrrev_i32_e32 v144, 6, v146
	v_cmp_le_i32_e32 vcc, v144, v224
	v_ashrrev_i32_e32 v144, 6, v147
	s_nop 0
	v_cndmask_b32_e32 v168, v216, v168, vcc
	v_cmp_le_i32_e32 vcc, v144, v224
	v_ashrrev_i32_e32 v144, 6, v148
	s_nop 0
	v_cndmask_b32_e32 v169, v216, v169, vcc
	v_cmp_le_i32_e32 vcc, v144, v224
	v_ashrrev_i32_e32 v144, 6, v149
	s_nop 0
	v_cndmask_b32_e32 v170, v216, v170, vcc
	v_cmp_le_i32_e32 vcc, v144, v224
	v_add_u32_e32 v144, 0x100c0, v227
	ds_read_b128 v[146:149], v144
	v_cndmask_b32_e32 v171, v216, v171, vcc
	s_waitcnt lgkmcnt(0)
	v_ashrrev_i32_e32 v144, 6, v146
	v_cmp_le_i32_e32 vcc, v144, v224
	v_ashrrev_i32_e32 v144, 6, v147
	s_nop 0
	v_cndmask_b32_e32 v172, v216, v172, vcc
	v_cmp_le_i32_e32 vcc, v144, v224
	v_ashrrev_i32_e32 v144, 6, v148
	s_nop 0
	v_cndmask_b32_e32 v173, v216, v173, vcc
	v_cmp_le_i32_e32 vcc, v144, v224
	v_ashrrev_i32_e32 v144, 6, v149
	s_nop 0
	v_cndmask_b32_e32 v174, v216, v174, vcc
	v_cmp_le_i32_e32 vcc, v144, v224
	v_add_u32_e32 v144, 0x100d0, v227
	ds_read_b128 v[146:149], v144
	v_cndmask_b32_e32 v175, v216, v175, vcc
	s_waitcnt lgkmcnt(0)
	v_ashrrev_i32_e32 v144, 6, v146
	v_cmp_le_i32_e32 vcc, v144, v224
	v_ashrrev_i32_e32 v144, 6, v147
	s_nop 0
	v_cndmask_b32_e32 v248, v216, v248, vcc
	v_cmp_le_i32_e32 vcc, v144, v224
	v_ashrrev_i32_e32 v144, 6, v148
	s_nop 0
	v_cndmask_b32_e32 v249, v216, v249, vcc
	v_cmp_le_i32_e32 vcc, v144, v224
	v_ashrrev_i32_e32 v144, 6, v149
	s_nop 0
	v_cndmask_b32_e32 v250, v216, v250, vcc
	v_cmp_le_i32_e32 vcc, v144, v224
	s_nop 1
	v_cndmask_b32_e32 v251, v216, v251, vcc
; #define MFMA(a, b, c) __builtin_amdgcn_mfma_f32_32x32x16_bf16((a), (b), (c), 0, 0, 0)
; DI u32 pk2(float a, float b) { f2_t v = {a, b}; bf2_t r = __builtin_convertvector(v, bf2_t); return __builtin_bit_cast(u32, r); }
; template <bool DIFF>
; DI void attn_phase(const AttnArgs& a, char* lds) {
;     ...
;           float ps = 0.f;
; #pragma unroll
;           for (int r = 0; r < 16; ++r) { s1[r] = __builtin_amdgcn_exp2f(s1[r]); ps += s1[r]; }
;           l_sum += ps;
;           asm volatile("" : "+v"(l_sum));
; #pragma unroll
;           for (int i = 0; i < 2 * NM; ++i) { __builtin_amdgcn_sched_group_barrier(0x008, 1, 0); __builtin_amdgcn_sched_group_barrier(0x002, 4, 0); }
;         }
;         __builtin_amdgcn_sched_barrier(0);
;         {
; #pragma unroll
;           for (int s2 = 0; s2 < 2; ++s2) {
;             bf16x8 vf[NM];
; #pragma unroll
;             for (int m = 0; m < NM; ++m) vf[m] = *(const bf16x8*)(sb + voffb + m * 4096 + (((4 + 2 * s2) ^ vx) << 4));
;             u32x4 pw;
;             pw[0] = pk2(s1[8 * s2], s1[8 * s2 + 1]); pw[1] = pk2(s1[8 * s2 + 2], s1[8 * s2 + 3]);
;             pw[2] = pk2(s1[8 * s2 + 4], s1[8 * s2 + 5]); pw[3] = pk2(s1[8 * s2 + 6], s1[8 * s2 + 7]);
;             const bf16x8 pf = __builtin_bit_cast(bf16x8, pw);
; #pragma unroll
;             for (int m = 0; m < NM; ++m) o[m] = MFMA(vf[m], pf, o[m]);
;           }
;         }
.LBB0_607:
	v_exp_f32_e32 v0, v164
	v_exp_f32_e32 v9, v165
	v_exp_f32_e32 v144, v166
	v_exp_f32_e32 v146, v167
	v_add_f32_e32 v2, 0, v0
	v_exp_f32_e32 v147, v168
	v_add_f32_e32 v2, v9, v2
	v_exp_f32_e32 v148, v169
	v_add_f32_e32 v2, v144, v2
	v_exp_f32_e32 v149, v170
	v_add_f32_e32 v2, v146, v2
	v_exp_f32_e32 v150, v171
	v_add_f32_e32 v2, v147, v2
	v_exp_f32_e32 v151, v172
	v_add_f32_e32 v2, v148, v2
	v_exp_f32_e32 v145, v173
	v_add_f32_e32 v2, v149, v2
	v_exp_f32_e32 v152, v174
	v_add_f32_e32 v2, v150, v2
	v_exp_f32_e32 v153, v175
	v_add_f32_e32 v2, v151, v2
	v_exp_f32_e32 v154, v248
	v_add_f32_e32 v2, v145, v2
	v_exp_f32_e32 v155, v249
	v_add_f32_e32 v2, v152, v2
	v_exp_f32_e32 v14, v250
	v_add_f32_e32 v2, v153, v2
	v_exp_f32_e32 v15, v251
	v_add_f32_e32 v2, v154, v2
	v_add_f32_e32 v2, v155, v2
	v_add_f32_e32 v2, v14, v2
	v_add_f32_e32 v2, v15, v2
	v_add_f32_e32 v226, v162, v2
	v_xad_u32 v156, v161, 64, v160
	ds_read_b128 v[2:5], v156 offset:32768
	ds_read_b128 v[228:231], v156 offset:36864
	ds_read_b128 v[232:235], v156 offset:40960
	ds_read_b128 v[236:239], v156 offset:45056
	ds_read_b128 v[240:243], v156 offset:49152
	ds_read_b128 v[244:247], v156 offset:53248
	ds_read_b128 v[248:251], v156 offset:57344
	v_cvt_pk_bf16_f32 v6, v0, v9
	v_cvt_pk_bf16_f32 v7, v144, v146
	v_cvt_pk_bf16_f32 v8, v147, v148
	v_cvt_pk_bf16_f32 v9, v149, v150
	v_xad_u32 v0, v161, s74, v160
	v_cvt_pk_bf16_f32 v10, v151, v145
	v_cvt_pk_bf16_f32 v11, v152, v153
	v_cvt_pk_bf16_f32 v12, v154, v155
	v_cvt_pk_bf16_f32 v13, v14, v15
	s_waitcnt lgkmcnt(6)
	v_mfma_f32_32x32x16_bf16 v[128:143], v[2:5], v[6:9], v[128:143]
	ds_read_b128 v[2:5], v156 offset:61440
	s_waitcnt lgkmcnt(6)
	v_mfma_f32_32x32x16_bf16 v[112:127], v[228:231], v[6:9], v[112:127]
	ds_read_b128 v[228:231], v0 offset:32768
	s_waitcnt lgkmcnt(6)
	v_mfma_f32_32x32x16_bf16 v[96:111], v[232:235], v[6:9], v[96:111]
	ds_read_b128 v[232:235], v0 offset:36864
	s_waitcnt lgkmcnt(6)
	v_mfma_f32_32x32x16_bf16 v[80:95], v[236:239], v[6:9], v[80:95]
	ds_read_b128 v[236:239], v0 offset:40960
	s_waitcnt lgkmcnt(6)
	v_mfma_f32_32x32x16_bf16 v[64:79], v[240:243], v[6:9], v[64:79]
	ds_read_b128 v[240:243], v0 offset:45056
	s_waitcnt lgkmcnt(6)
	v_mfma_f32_32x32x16_bf16 v[48:63], v[244:247], v[6:9], v[48:63]
	ds_read_b128 v[244:247], v0 offset:49152
	s_waitcnt lgkmcnt(6)
	v_mfma_f32_32x32x16_bf16 v[32:47], v[248:251], v[6:9], v[32:47]
	ds_read_b128 v[248:251], v0 offset:53248
	s_waitcnt lgkmcnt(6)
	v_mfma_f32_32x32x16_bf16 v[16:31], v[2:5], v[6:9], v[16:31]
	ds_read_b128 v[2:5], v0 offset:57344
	s_waitcnt lgkmcnt(6)
	v_mfma_f32_32x32x16_bf16 v[128:143], v[228:231], v[10:13], v[128:143]
	ds_read_b128 v[228:231], v0 offset:61440
	s_waitcnt lgkmcnt(6)
	v_mfma_f32_32x32x16_bf16 v[112:127], v[232:235], v[10:13], v[112:127]
	s_waitcnt lgkmcnt(5)
	v_mfma_f32_32x32x16_bf16 v[96:111], v[236:239], v[10:13], v[96:111]
	s_waitcnt lgkmcnt(4)
	v_mfma_f32_32x32x16_bf16 v[80:95], v[240:243], v[10:13], v[80:95]
	s_waitcnt lgkmcnt(3)
	v_mfma_f32_32x32x16_bf16 v[64:79], v[244:247], v[10:13], v[64:79]
	s_waitcnt lgkmcnt(2)
	v_mfma_f32_32x32x16_bf16 v[48:63], v[248:251], v[10:13], v[48:63]
	s_waitcnt lgkmcnt(1)
	v_mfma_f32_32x32x16_bf16 v[32:47], v[2:5], v[10:13], v[32:47]
	s_waitcnt lgkmcnt(0)
	v_mfma_f32_32x32x16_bf16 v[16:31], v[228:231], v[10:13], v[16:31]
